# attention output epilogues: 16 sub-LN gain loads issued together, v_permlane32_swap so each lane stores 16 B (8 dwordx4 instead of 16 dwordx2), bit-identical outputs
# speedup vs baseline: 1.0611x; 1.0011x over previous
; __device__ __forceinline__ unsigned cvtpk(float lo, float hi) { const f32x2_t v = {lo, hi}; const bf16x2_t b = __builtin_convertvector(v, bf16x2_t); return __builtin_bit_cast(unsigned, b); }
; __device__ __forceinline__ int otid() { int t = threadIdx.x; asm volatile("" : "+v"(t)); return t; }
; __device__ __forceinline__ void attn_phase(const AttnPtrs& P, bool do_ctx, LAS unsigned char* lds) {
;     ...
;                 const int tid2 = otid();
;                 bf16_t* op = O + (size_t)(row0 + (tid2 >> 6) * 32 + (tid2 & 31)) * 512 + h * 64 + 4 * ((tid2 & 63) >> 5);
; #pragma unroll
;                 for (int rb = 0; rb < 2; ++rb)
; #pragma unroll
;                     for (int i = 0; i < 2; ++i)
; #pragma unroll
;                         for (int g = 0; g < 4; ++g) { u32x2 w; w.x = cvtpk(o[rb][i][4 * g], o[rb][i][4 * g + 1]); w.y = cvtpk(o[rb][i][4 * g + 2], o[rb][i][4 * g + 3]); *(u32x2*)(op + 64 * rb + 32 * i + 8 * g) = w; }
.LBB0_416:
	s_nop 0
	v_ashrrev_i32_e32 v32, 1, v0
	v_and_b32_e32 v32, 0xffffffe0, v32
	v_and_b32_e32 v33, 31, v0
	s_mul_i32 s2, s14, 0x1080000
	v_readlane_b32 s6, v255, 24
	v_add3_u32 v32, v33, s15, v32
	s_mul_hi_u32 s1, s14, 0x1080000
	v_readlane_b32 s7, v255, 25
	s_add_u32 s2, s6, s2
	v_ashrrev_i32_e32 v33, 31, v32
	s_addc_u32 s3, s7, s1
	v_lshlrev_b64 v[32:33], 10, v[32:33]
	v_lshl_add_u64 v[32:33], s[2:3], 0, v[32:33]
	v_lshrrev_b32_e32 v0, 1, v0
	v_lshl_add_u64 v[32:33], s[4:5], 1, v[32:33]
	v_and_b32_e32 v0, 16, v0
	v_lshl_add_u64 v[32:33], v[32:33], 0, v[0:1]
	v_cvt_pk_bf16_f32 v88, v2, v3
	v_cvt_pk_bf16_f32 v89, v4, v5
	v_cvt_pk_bf16_f32 v90, v6, v7
	v_cvt_pk_bf16_f32 v91, v8, v9
	s_nop 1
	v_permlane32_swap_b32_e32 v88, v90
	v_permlane32_swap_b32_e32 v89, v91
	global_store_dwordx4 v[32:33], v[88:91], off
	v_cvt_pk_bf16_f32 v92, v10, v11
	v_cvt_pk_bf16_f32 v93, v12, v13
	v_cvt_pk_bf16_f32 v94, v14, v15
	v_cvt_pk_bf16_f32 v95, v80, v81
	s_nop 1
	v_permlane32_swap_b32_e32 v92, v94
	v_permlane32_swap_b32_e32 v93, v95
	global_store_dwordx4 v[32:33], v[92:95], off offset:32
	v_cvt_pk_bf16_f32 v88, v48, v49
	v_cvt_pk_bf16_f32 v89, v82, v83
	v_cvt_pk_bf16_f32 v90, v66, v67
	v_cvt_pk_bf16_f32 v91, v64, v65
	s_nop 1
	v_permlane32_swap_b32_e32 v88, v90
	v_permlane32_swap_b32_e32 v89, v91
	global_store_dwordx4 v[32:33], v[88:91], off offset:64
	v_cvt_pk_bf16_f32 v92, v50, v51
	v_cvt_pk_bf16_f32 v93, v56, v57
	v_cvt_pk_bf16_f32 v94, v54, v55
	v_cvt_pk_bf16_f32 v95, v52, v53
	s_nop 1
	v_permlane32_swap_b32_e32 v92, v94
	v_permlane32_swap_b32_e32 v93, v95
	global_store_dwordx4 v[32:33], v[92:95], off offset:96
	v_cvt_pk_bf16_f32 v88, v58, v59
	v_cvt_pk_bf16_f32 v89, v60, v61
	v_cvt_pk_bf16_f32 v90, v62, v63
	v_cvt_pk_bf16_f32 v91, v68, v69
	s_nop 1
	v_permlane32_swap_b32_e32 v88, v90
	v_permlane32_swap_b32_e32 v89, v91
	global_store_dwordx4 v[32:33], v[88:91], off offset:128
	v_cvt_pk_bf16_f32 v92, v70, v71
	v_cvt_pk_bf16_f32 v93, v72, v73
	v_cvt_pk_bf16_f32 v94, v74, v75
	v_cvt_pk_bf16_f32 v95, v76, v77
	s_nop 1
	v_permlane32_swap_b32_e32 v92, v94
	v_permlane32_swap_b32_e32 v93, v95
	global_store_dwordx4 v[32:33], v[92:95], off offset:160
	v_cvt_pk_bf16_f32 v88, v16, v17
	v_cvt_pk_bf16_f32 v89, v18, v19
	v_cvt_pk_bf16_f32 v90, v20, v21
	v_cvt_pk_bf16_f32 v91, v22, v23
	s_nop 1
	v_permlane32_swap_b32_e32 v88, v90
	v_permlane32_swap_b32_e32 v89, v91
	global_store_dwordx4 v[32:33], v[88:91], off offset:192
	v_cvt_pk_bf16_f32 v92, v24, v25
	v_cvt_pk_bf16_f32 v93, v26, v27
	v_cvt_pk_bf16_f32 v94, v28, v29
	v_cvt_pk_bf16_f32 v95, v30, v31
	s_nop 1
	v_permlane32_swap_b32_e32 v92, v94
	v_permlane32_swap_b32_e32 v93, v95
	global_store_dwordx4 v[32:33], v[92:95], off offset:224
	s_branch .LBB0_350

; __device__ __forceinline__ unsigned cvtpk(float lo, float hi) { const f32x2_t v = {lo, hi}; const bf16x2_t b = __builtin_convertvector(v, bf16x2_t); return __builtin_bit_cast(unsigned, b); }
; __device__ __forceinline__ void attn_phase(const AttnPtrs& P, bool do_ctx, LAS unsigned char* lds) {
;     ...
;                     ss += __shfl_xor(ss, 32);
;                     const float sc = rsqrtf(ss * (1.f / 128.f) + 1e-5f) * (1.f - lam_init_of(ly_));
;                     bf16_t* op = P.OA + (size_t)myrow * 512 + h * 128 + 4 * hi;
; #pragma unroll
;                     for (int i = 0; i < 4; ++i)
; #pragma unroll
;                         for (int g = 0; g < 4; ++g) {
;                             const f32x4 gs = *(const f32x4*)(P.gsub + 32 * i + 8 * g + 4 * hi);
;                             u32x2 w; w.x = cvtpk(o[i][4 * g] * sc * gs[0], o[i][4 * g + 1] * sc * gs[1]); w.y = cvtpk(o[i][4 * g + 2] * sc * gs[2], o[i][4 * g + 3] * sc * gs[3]);
;                             *(u32x2*)(op + 32 * i + 8 * g) = w;
.LBB0_446:
	s_waitcnt lgkmcnt(0)
	v_add_f32_e32 v0, v0, v130
	v_mov_b32_e32 v130, 0x3727c5ac
	v_fmamk_f32 v0, v0, 0x3c000000, v130
	v_cmp_gt_f32_e32 vcc, s41, v0
	v_mul_f32_e32 v130, 0x4b800000, v0
	s_mov_b64 s[20:21], 0
	v_cndmask_b32_e32 v0, v0, v130, vcc
	v_rsq_f32_e32 v0, v0
	s_nop 0
	v_mul_f32_e32 v130, 0x45800000, v0
	v_cndmask_b32_e32 v0, v0, v130, vcc
	v_sub_f32_e32 v130, 1.0, v131
	v_mul_f32_e32 v0, v0, v130
	global_load_dwordx4 v[130:133], v[178:179], off
	global_load_dwordx4 v[134:137], v[178:179], off offset:32
	global_load_dwordx4 v[138:141], v[178:179], off offset:64
	global_load_dwordx4 v[142:145], v[178:179], off offset:96
	global_load_dwordx4 v[146:149], v[178:179], off offset:128
	global_load_dwordx4 v[150:153], v[178:179], off offset:160
	global_load_dwordx4 v[154:157], v[178:179], off offset:192
	global_load_dwordx4 v[158:161], v[178:179], off offset:224
	global_load_dwordx4 v[162:165], v[178:179], off offset:256
	global_load_dwordx4 v[166:169], v[178:179], off offset:288
	global_load_dwordx4 v[170:173], v[178:179], off offset:320
	global_load_dwordx4 v[198:201], v[178:179], off offset:352
	global_load_dwordx4 v[202:205], v[178:179], off offset:384
	global_load_dwordx4 v[206:209], v[178:179], off offset:416
	global_load_dwordx4 v[210:213], v[178:179], off offset:448
	global_load_dwordx4 v[214:217], v[178:179], off offset:480
	v_lshrrev_b32_e32 v218, 2, v253
	v_and_b32_e32 v218, 8, v218
	v_mov_b32_e32 v219, 0
	v_lshl_add_u64 v[176:177], v[176:177], 0, v[218:219]
	v_pk_mul_f32 v[128:129], v[128:129], v[0:1] op_sel_hi:[1,0]
	v_pk_mul_f32 v[126:127], v[126:127], v[0:1] op_sel_hi:[1,0]
	v_pk_mul_f32 v[124:125], v[124:125], v[0:1] op_sel_hi:[1,0]
	v_pk_mul_f32 v[122:123], v[122:123], v[0:1] op_sel_hi:[1,0]
	v_pk_mul_f32 v[120:121], v[120:121], v[0:1] op_sel_hi:[1,0]
	v_pk_mul_f32 v[118:119], v[118:119], v[0:1] op_sel_hi:[1,0]
	v_pk_mul_f32 v[116:117], v[116:117], v[0:1] op_sel_hi:[1,0]
	v_pk_mul_f32 v[114:115], v[114:115], v[0:1] op_sel_hi:[1,0]
	v_pk_mul_f32 v[112:113], v[112:113], v[0:1] op_sel_hi:[1,0]
	v_pk_mul_f32 v[110:111], v[110:111], v[0:1] op_sel_hi:[1,0]
	v_pk_mul_f32 v[108:109], v[108:109], v[0:1] op_sel_hi:[1,0]
	v_pk_mul_f32 v[106:107], v[106:107], v[0:1] op_sel_hi:[1,0]
	v_pk_mul_f32 v[104:105], v[104:105], v[0:1] op_sel_hi:[1,0]
	v_pk_mul_f32 v[102:103], v[102:103], v[0:1] op_sel_hi:[1,0]
	v_pk_mul_f32 v[100:101], v[100:101], v[0:1] op_sel_hi:[1,0]
	v_pk_mul_f32 v[98:99], v[98:99], v[0:1] op_sel_hi:[1,0]
	v_pk_mul_f32 v[96:97], v[96:97], v[0:1] op_sel_hi:[1,0]
	v_pk_mul_f32 v[94:95], v[94:95], v[0:1] op_sel_hi:[1,0]
	v_pk_mul_f32 v[92:93], v[92:93], v[0:1] op_sel_hi:[1,0]
	v_pk_mul_f32 v[90:91], v[90:91], v[0:1] op_sel_hi:[1,0]
	v_pk_mul_f32 v[88:89], v[88:89], v[0:1] op_sel_hi:[1,0]
	v_pk_mul_f32 v[86:87], v[86:87], v[0:1] op_sel_hi:[1,0]
	v_pk_mul_f32 v[84:85], v[84:85], v[0:1] op_sel_hi:[1,0]
	v_pk_mul_f32 v[82:83], v[82:83], v[0:1] op_sel_hi:[1,0]
	v_pk_mul_f32 v[80:81], v[80:81], v[0:1] op_sel_hi:[1,0]
	v_pk_mul_f32 v[78:79], v[78:79], v[0:1] op_sel_hi:[1,0]
	v_pk_mul_f32 v[76:77], v[76:77], v[0:1] op_sel_hi:[1,0]
	v_pk_mul_f32 v[74:75], v[74:75], v[0:1] op_sel_hi:[1,0]
	v_pk_mul_f32 v[72:73], v[72:73], v[0:1] op_sel_hi:[1,0]
	v_pk_mul_f32 v[70:71], v[70:71], v[0:1] op_sel_hi:[1,0]
	v_pk_mul_f32 v[68:69], v[68:69], v[0:1] op_sel_hi:[1,0]
	v_pk_mul_f32 v[66:67], v[66:67], v[0:1] op_sel_hi:[1,0]
	s_waitcnt vmcnt(0)
; __device__ __forceinline__ unsigned cvtpk(float lo, float hi) { const f32x2_t v = {lo, hi}; const bf16x2_t b = __builtin_convertvector(v, bf16x2_t); return __builtin_bit_cast(unsigned, b); }
; __device__ __forceinline__ void attn_phase(const AttnPtrs& P, bool do_ctx, LAS unsigned char* lds) {
;     ...
;                     bf16_t* op = P.OA + (size_t)myrow * 512 + h * 128 + 4 * hi;
; #pragma unroll
;                     for (int i = 0; i < 4; ++i)
; #pragma unroll
;                         for (int g = 0; g < 4; ++g) {
;                             const f32x4 gs = *(const f32x4*)(P.gsub + 32 * i + 8 * g + 4 * hi);
;                             u32x2 w; w.x = cvtpk(o[i][4 * g] * sc * gs[0], o[i][4 * g + 1] * sc * gs[1]); w.y = cvtpk(o[i][4 * g + 2] * sc * gs[2], o[i][4 * g + 3] * sc * gs[3]);
;                             *(u32x2*)(op + 32 * i + 8 * g) = w;
	v_pk_mul_f32 v[128:129], v[128:129], v[130:131]
	v_pk_mul_f32 v[126:127], v[126:127], v[132:133]
	v_pk_mul_f32 v[124:125], v[124:125], v[134:135]
	v_pk_mul_f32 v[122:123], v[122:123], v[136:137]
	v_cvt_pk_bf16_f32 v194, v128, v129
	v_cvt_pk_bf16_f32 v195, v126, v127
	v_cvt_pk_bf16_f32 v196, v124, v125
	v_cvt_pk_bf16_f32 v197, v122, v123
	s_nop 1
	v_permlane32_swap_b32_e32 v194, v196
	v_permlane32_swap_b32_e32 v195, v197
	global_store_dwordx4 v[176:177], v[194:197], off
	v_pk_mul_f32 v[120:121], v[120:121], v[138:139]
	v_pk_mul_f32 v[118:119], v[118:119], v[140:141]
	v_pk_mul_f32 v[116:117], v[116:117], v[142:143]
	v_pk_mul_f32 v[114:115], v[114:115], v[144:145]
	v_cvt_pk_bf16_f32 v218, v120, v121
	v_cvt_pk_bf16_f32 v219, v118, v119
	v_cvt_pk_bf16_f32 v220, v116, v117
	v_cvt_pk_bf16_f32 v221, v114, v115
	s_nop 1
	v_permlane32_swap_b32_e32 v218, v220
	v_permlane32_swap_b32_e32 v219, v221
	global_store_dwordx4 v[176:177], v[218:221], off offset:32
	v_pk_mul_f32 v[112:113], v[112:113], v[146:147]
	v_pk_mul_f32 v[110:111], v[110:111], v[148:149]
	v_pk_mul_f32 v[108:109], v[108:109], v[150:151]
	v_pk_mul_f32 v[106:107], v[106:107], v[152:153]
	v_cvt_pk_bf16_f32 v194, v112, v113
	v_cvt_pk_bf16_f32 v195, v110, v111
	v_cvt_pk_bf16_f32 v196, v108, v109
	v_cvt_pk_bf16_f32 v197, v106, v107
	s_nop 1
	v_permlane32_swap_b32_e32 v194, v196
	v_permlane32_swap_b32_e32 v195, v197
	global_store_dwordx4 v[176:177], v[194:197], off offset:64
	v_pk_mul_f32 v[104:105], v[104:105], v[154:155]
	v_pk_mul_f32 v[102:103], v[102:103], v[156:157]
	v_pk_mul_f32 v[100:101], v[100:101], v[158:159]
	v_pk_mul_f32 v[98:99], v[98:99], v[160:161]
	v_cvt_pk_bf16_f32 v218, v104, v105
	v_cvt_pk_bf16_f32 v219, v102, v103
	v_cvt_pk_bf16_f32 v220, v100, v101
	v_cvt_pk_bf16_f32 v221, v98, v99
	s_nop 1
	v_permlane32_swap_b32_e32 v218, v220
	v_permlane32_swap_b32_e32 v219, v221
	global_store_dwordx4 v[176:177], v[218:221], off offset:96
	v_pk_mul_f32 v[96:97], v[96:97], v[162:163]
	v_pk_mul_f32 v[94:95], v[94:95], v[164:165]
	v_pk_mul_f32 v[92:93], v[92:93], v[166:167]
	v_pk_mul_f32 v[86:87], v[86:87], v[168:169]
	v_cvt_pk_bf16_f32 v194, v96, v97
	v_cvt_pk_bf16_f32 v195, v94, v95
	v_cvt_pk_bf16_f32 v196, v92, v93
	v_cvt_pk_bf16_f32 v197, v86, v87
	s_nop 1
	v_permlane32_swap_b32_e32 v194, v196
	v_permlane32_swap_b32_e32 v195, v197
	global_store_dwordx4 v[176:177], v[194:197], off offset:128
	v_pk_mul_f32 v[90:91], v[90:91], v[170:171]
	v_pk_mul_f32 v[88:89], v[88:89], v[172:173]
	v_pk_mul_f32 v[84:85], v[84:85], v[198:199]
	v_pk_mul_f32 v[82:83], v[82:83], v[200:201]
	v_cvt_pk_bf16_f32 v218, v90, v91
	v_cvt_pk_bf16_f32 v219, v88, v89
	v_cvt_pk_bf16_f32 v220, v84, v85
	v_cvt_pk_bf16_f32 v221, v82, v83
	s_nop 1
	v_permlane32_swap_b32_e32 v218, v220
	v_permlane32_swap_b32_e32 v219, v221
	global_store_dwordx4 v[176:177], v[218:221], off offset:160
	v_pk_mul_f32 v[80:81], v[80:81], v[202:203]
	v_pk_mul_f32 v[78:79], v[78:79], v[204:205]
	v_pk_mul_f32 v[76:77], v[76:77], v[206:207]
	v_pk_mul_f32 v[74:75], v[74:75], v[208:209]
	v_cvt_pk_bf16_f32 v194, v80, v81
	v_cvt_pk_bf16_f32 v195, v78, v79
	v_cvt_pk_bf16_f32 v196, v76, v77
	v_cvt_pk_bf16_f32 v197, v74, v75
	s_nop 1
	v_permlane32_swap_b32_e32 v194, v196
	v_permlane32_swap_b32_e32 v195, v197
	global_store_dwordx4 v[176:177], v[194:197], off offset:192
	v_pk_mul_f32 v[72:73], v[72:73], v[210:211]
	v_pk_mul_f32 v[70:71], v[70:71], v[212:213]
	v_pk_mul_f32 v[68:69], v[68:69], v[214:215]
	v_pk_mul_f32 v[66:67], v[66:67], v[216:217]
	v_cvt_pk_bf16_f32 v218, v72, v73
	v_cvt_pk_bf16_f32 v219, v70, v71
	v_cvt_pk_bf16_f32 v220, v68, v69
	v_cvt_pk_bf16_f32 v221, v66, v67
	s_nop 1
	v_permlane32_swap_b32_e32 v218, v220
	v_permlane32_swap_b32_e32 v219, v221
	global_store_dwordx4 v[176:177], v[218:221], off offset:224
